# v82 + DSA attention score scaling folded (s*(0.125*log2e), min 60*log2e): one multiply less per score, bit-identical
# speedup vs baseline: 1.0020x; 1.0020x over previous
.LBB0_1028:
	s_cmp_ge_i32 s20, s14
	s_cbranch_scc1 .LBB0_1027
	ds_read_b128 v[68:71], v131
	ds_read_b128 v[72:75], v131 offset:64
	v_add_u32_e32 v140, s11, v129
	v_add_u32_e32 v80, 0x3000, v130
	s_waitcnt vmcnt(3) lgkmcnt(1)
	v_mfma_f32_16x16x32_bf16 v[76:79], v[68:71], v[36:39], 0
	s_waitcnt vmcnt(1)
	v_mfma_f32_16x16x32_bf16 v[68:71], v[68:71], v[44:47], 0
	s_waitcnt lgkmcnt(0)
	v_mfma_f32_16x16x32_bf16 v[132:135], v[72:75], v[40:43], v[76:79]
	s_waitcnt vmcnt(0)
	v_mfma_f32_16x16x32_bf16 v[88:91], v[72:75], v[48:51], v[68:71]
	s_nop 3
	ds_read_b128 v[68:71], v131 offset:2304
	ds_read_b128 v[72:75], v131 offset:2368
	ds_read_b32 v140, v140
	v_mul_f32_e32 v132, 0x3e38aa3b, v132
	s_waitcnt lgkmcnt(2)
	v_mfma_f32_16x16x32_bf16 v[76:79], v[68:71], v[36:39], 0
	v_min_f32_e32 v132, 0x42ad1f97, v132
	v_mul_f32_e32 v133, 0x3e38aa3b, v133
	ds_read2_b64 v[80:83], v80 offset0:96 offset1:100
	v_mfma_f32_16x16x32_bf16 v[68:71], v[68:71], v[44:47], 0
	v_min_f32_e32 v133, 0x42ad1f97, v133
	v_mul_f32_e32 v134, 0x3e38aa3b, v134
	s_waitcnt lgkmcnt(2)
	v_mfma_f32_16x16x32_bf16 v[136:139], v[72:75], v[40:43], v[76:79]
	v_exp_f32_e32 v132, v132
	v_min_f32_e32 v134, 0x42ad1f97, v134
	v_mfma_f32_16x16x32_bf16 v[84:87], v[72:75], v[48:51], v[68:71]
	ds_read2_b64 v[76:79], v130 offset1:4
	v_mul_f32_e32 v135, 0x3e38aa3b, v135
	v_mul_f32_e32 v88, 0x3e38aa3b, v88
	v_add_u32_e32 v68, 0x1000, v130
	ds_read2_b64 v[72:75], v68 offset0:32 offset1:36
	v_add_u32_e32 v68, 0x2000, v130
	ds_read2_b64 v[68:71], v68 offset0:64 offset1:68
	v_exp_f32_e32 v133, v133
	s_waitcnt lgkmcnt(4)
	v_and_b32_e32 v142, v140, v117
	v_min_f32_e32 v135, 0x42ad1f97, v135
	v_mul_f32_e32 v136, 0x3e38aa3b, v136
	v_mul_f32_e32 v137, 0x3e38aa3b, v137
	v_mul_f32_e32 v138, 0x3e38aa3b, v138
	v_mul_f32_e32 v139, 0x3e38aa3b, v139
	v_min_f32_e32 v88, 0x42ad1f97, v88
	v_mul_f32_e32 v89, 0x3e38aa3b, v89
	v_and_b32_e32 v141, v140, v116
	v_cmp_eq_u32_e64 s[6:7], 0, v142
	v_exp_f32_e32 v134, v134
	v_and_b32_e32 v142, v140, v118
	v_min_f32_e32 v136, 0x42ad1f97, v136
	v_min_f32_e32 v137, 0x42ad1f97, v137
	v_min_f32_e32 v138, 0x42ad1f97, v138
	v_min_f32_e32 v139, 0x42ad1f97, v139
	v_min_f32_e32 v89, 0x42ad1f97, v89
	v_mul_f32_e32 v90, 0x3e38aa3b, v90
	v_cmp_eq_u32_e32 vcc, 0, v141
	v_cmp_eq_u32_e64 s[0:1], 0, v142
	v_exp_f32_e32 v135, v135
	v_and_b32_e32 v142, v140, v119
	v_exp_f32_e32 v88, v88
	v_min_f32_e32 v90, 0x42ad1f97, v90
	v_mul_f32_e32 v91, 0x3e38aa3b, v91
	v_cndmask_b32_e64 v132, v132, 0, vcc
	v_cmp_eq_u32_e64 s[4:5], 0, v142
	v_exp_f32_e32 v136, v136
	v_and_b32_e32 v142, v140, v120
	v_exp_f32_e32 v137, v137
	v_exp_f32_e32 v138, v138
	v_exp_f32_e32 v139, v139
	v_exp_f32_e32 v89, v89
	v_min_f32_e32 v91, 0x42ad1f97, v91
	v_mul_f32_e32 v84, 0x3e38aa3b, v84
	v_add_f32_e32 v141, 0, v132
	v_cndmask_b32_e64 v133, v133, 0, s[6:7]
	v_cmp_eq_u32_e64 s[40:41], 0, v142
	v_and_b32_e32 v142, v140, v121
	v_exp_f32_e32 v90, v90
	v_min_f32_e32 v84, 0x42ad1f97, v84
	v_mul_f32_e32 v85, 0x3e38aa3b, v85
	v_add_f32_e32 v141, v133, v141
	v_cndmask_b32_e64 v134, v134, 0, s[0:1]
	v_cmp_eq_u32_e64 s[46:47], 0, v142
	v_and_b32_e32 v142, v140, v122
	v_and_b32_e32 v140, v140, v123
	v_exp_f32_e32 v91, v91
	v_min_f32_e32 v85, 0x42ad1f97, v85
	v_add_f32_e32 v141, v134, v141
	v_cndmask_b32_e64 v135, v135, 0, s[4:5]
	v_cmp_eq_u32_e64 s[42:43], 0, v142
	v_cmp_eq_u32_e64 s[44:45], 0, v140
	v_cvt_pk_bf16_f32 v132, v132, v133
	v_cndmask_b32_e64 v88, v88, 0, vcc
	v_exp_f32_e32 v84, v84
	v_add_f32_e32 v141, v135, v141
	v_cndmask_b32_e64 v136, v136, 0, s[40:41]
	v_cndmask_b32_e64 v137, v137, 0, s[46:47]
	v_cndmask_b32_e64 v138, v138, 0, s[42:43]
	v_cndmask_b32_e64 v139, v139, 0, s[44:45]
	v_cvt_pk_bf16_f32 v133, v134, v135
	v_cvt_pk_bf16_f32 v134, v136, v137
	v_cvt_pk_bf16_f32 v135, v138, v139
	v_cndmask_b32_e64 v89, v89, 0, s[6:7]
	s_waitcnt lgkmcnt(2)
	v_mfma_f32_16x16x32_bf16 v[32:35], v[76:79], v[132:135], v[32:35]
	v_exp_f32_e32 v85, v85
	v_cndmask_b32_e64 v90, v90, 0, s[0:1]
	v_cndmask_b32_e64 v91, v91, 0, s[4:5]
	s_waitcnt lgkmcnt(1)
	v_mfma_f32_16x16x32_bf16 v[24:27], v[72:75], v[132:135], v[24:27]
	v_add_f32_e32 v141, v136, v141
	v_add_f32_e32 v141, v137, v141
	v_add_f32_e32 v141, v138, v141
	s_waitcnt lgkmcnt(0)
	v_mfma_f32_16x16x32_bf16 v[16:19], v[68:71], v[132:135], v[16:19]
	v_add_f32_e32 v140, v139, v141
	v_add_f32_e32 v128, v128, v140
	v_mfma_f32_16x16x32_bf16 v[20:23], v[80:83], v[132:135], v[20:23]
	v_add_f32_e32 v132, 0, v88
	v_add_f32_e32 v132, v89, v132
	v_add_f32_e32 v132, v90, v132
	v_add_f32_e32 v132, v91, v132
	v_cndmask_b32_e64 v133, v84, 0, s[40:41]
	v_add_f32_e32 v84, v133, v132
	v_cndmask_b32_e64 v132, v85, 0, s[46:47]
	v_mul_f32_e32 v85, 0x3e38aa3b, v86
	v_min_f32_e32 v85, 0x42ad1f97, v85
	v_exp_f32_e32 v85, v85
	v_add_f32_e32 v84, v132, v84
	v_cndmask_b32_e64 v134, v85, 0, s[42:43]
	v_mul_f32_e32 v85, 0x3e38aa3b, v87
	v_min_f32_e32 v85, 0x42ad1f97, v85
	v_exp_f32_e32 v85, v85
	v_add_f32_e32 v84, v134, v84
	v_cndmask_b32_e64 v87, v85, 0, s[44:45]
	v_add_f32_e32 v84, v87, v84
	v_add_f32_e32 v127, v127, v84
	v_cvt_pk_bf16_f32 v84, v88, v89
	v_cvt_pk_bf16_f32 v85, v90, v91
	v_cvt_pk_bf16_f32 v86, v133, v132
	v_cvt_pk_bf16_f32 v87, v134, v87
	s_nop 0
	v_mfma_f32_16x16x32_bf16 v[8:11], v[76:79], v[84:87], v[8:11]
	v_mfma_f32_16x16x32_bf16 v[12:15], v[72:75], v[84:87], v[12:15]
	v_mfma_f32_16x16x32_bf16 v[4:7], v[68:71], v[84:87], v[4:7]
	v_mfma_f32_16x16x32_bf16 v[0:3], v[80:83], v[84:87], v[0:3]
	s_branch .LBB0_1027
